# key-norm table producer spread over the gMLP phase (loads first, atomics before the LN barrier, counters after the epilogue wait)
# speedup vs baseline: 1.0618x; 1.0050x over previous
.LBB0_543:
	s_and_b64 vcc, exec, s[38:39]
	s_nop 0
	s_nop 0
	s_load_dwordx2 s[34:35], s[0:1], 32
	s_waitcnt lgkmcnt(0)
	s_load_dwordx2 s[28:29], s[0:1], 40
	s_waitcnt lgkmcnt(0)
	s_load_dwordx2 s[30:31], s[0:1], 48
	s_waitcnt lgkmcnt(0)
	s_load_dwordx2 s[22:23], s[0:1], 56
	s_waitcnt lgkmcnt(0)
	s_nop 0
	s_nop 0
	s_nop 0
	s_nop 0
	s_nop 0
	s_load_dwordx2 s[10:11], s[0:1], 0x60
	s_waitcnt lgkmcnt(0)
	s_load_dwordx2 s[26:27], s[0:1], 0x68
	s_waitcnt lgkmcnt(0)
	s_cbranch_vccnz .LBB0_554
	v_readlane_b32 s100, v252, 9
	s_nop 3
	s_lshr_b32 s101, s100, 3
	s_and_b32 s100, s100, 7
	s_lshr_b32 s2, s101, 3
	s_and_b32 s3, s101, 7
	s_lshl_b32 s2, s2, 12
	s_lshl_b32 s20, s100, 9
	s_add_i32 s2, s2, s20
	s_mul_i32 s20, s2, 0x1e00
	s_lshl_b32 s3, s3, 7
	s_add_u32 s20, s20, s3
	s_add_u32 s20, s20, 0x7001200
	s_add_u32 s2, s26, s20
	s_addc_u32 s3, s27, 0
	v_lshrrev_b32_e32 v242, 3, v184
	v_mul_u32_u24_e32 v242, 0x1e00, v242
	v_and_b32_e32 v243, 7, v184
	v_lshl_add_u32 v242, v243, 4, v242
	global_load_dwordx4 v[202:205], v242, s[2:3]
	v_add_u32_e32 v243, 0x78000, v242
	global_load_dwordx4 v[206:209], v243, s[2:3]
	v_add_u32_e32 v243, 0xf0000, v242
	global_load_dwordx4 v[210:213], v243, s[2:3]
	v_add_u32_e32 v243, 0x168000, v242
	global_load_dwordx4 v[214:217], v243, s[2:3]
	v_add_u32_e32 v243, 0x1e0000, v242
	global_load_dwordx4 v[218:221], v243, s[2:3]
	v_add_u32_e32 v243, 0x258000, v242
	global_load_dwordx4 v[230:233], v243, s[2:3]
	v_add_u32_e32 v243, 0x2d0000, v242
	global_load_dwordx4 v[234:237], v243, s[2:3]
	v_add_u32_e32 v243, 0x348000, v242
	global_load_dwordx4 v[238:241], v243, s[2:3]
	s_lshl_b32 s2, s101, 6
	s_lshl_b32 s3, s16, 11
	s_add_i32 s2, s2, s3
	s_getpc_b64 s[100:101]
	s_add_u32 s100, s100, g_ctl@rel32@lo+51204
	s_addc_u32 s101, s101, g_ctl@rel32@hi+51212
	s_add_u32 s100, s100, s2
	s_addc_u32 s101, s101, 0
	s_add_u32 s24, s26, 0x4000000
	s_addc_u32 s25, s27, 0
	v_readlane_b32 s2, v252, 24
	s_add_u32 s26, s26, 0x7000000
	v_readlane_b32 s3, v252, 25
	s_addc_u32 s27, s27, 0
	s_lshl_b64 s[10:11], s[2:3], 2
	s_add_u32 s18, s34, s10
	s_addc_u32 s19, s35, s11
	s_add_u32 s28, s28, s10
	s_addc_u32 s29, s29, s11
	s_lshl_b32 s10, s16, 2
	s_add_u32 s30, s30, 16
	v_readlane_b32 s2, v252, 9
	s_addc_u32 s31, s31, 0
	s_lshl_b32 s11, s16, 9
	s_mov_b32 s12, s2
	s_mov_b32 s13, s2
	v_readlane_b32 s3, v252, 10
	s_branch .LBB0_546
.LBB0_545:
	s_or_b64 exec, exec, s[34:35]
	s_or_b32 s2, s14, s10
	s_lshl_b32 s80, s2, 7
	v_lshl_add_u64 v[12:13], s[80:81], 2, v[22:23]
	global_load_dwordx4 v[12:15], v[12:13], off
	v_lshlrev_b32_e32 v22, 16, v109
	v_mov_b32_e32 v33, v191
	v_lshl_add_u64 v[20:21], s[24:25], 0, v[32:33]
	v_or_b32_e32 v190, 32, v32
	s_add_i32 s13, s13, s72
	s_sub_i32 s12, s12, s72
	s_cmpk_gt_i32 s13, 0x1ff
	s_waitcnt vmcnt(0)
	s_mov_b64 exec, 0xff
	global_atomic_add v248, v193, s[100:101] offset:4
	s_mov_b64 exec, -1
	v_add_f32_e32 v16, v16, v12
	v_mul_f32_e32 v16, v16, v22
	v_lshlrev_b32_e32 v22, 16, v108
	v_mul_f32_e32 v16, v16, v22
	v_lshlrev_b64 v[22:23], 11, v[34:35]
	v_cvt_pk_bf16_f32 v16, v16, s0
	v_lshl_add_u64 v[24:25], v[20:21], 0, v[22:23]
	global_store_short v[24:25], v16, off
	v_add_f32_e32 v16, v17, v13
	v_lshlrev_b32_e32 v17, 16, v107
	v_mul_f32_e32 v16, v16, v17
	v_lshlrev_b32_e32 v17, 16, v106
	v_mul_f32_e32 v16, v16, v17
	v_or_b32_e32 v24, 0x800, v22
	v_mov_b32_e32 v25, v23
	v_cvt_pk_bf16_f32 v26, v16, s0
	v_lshl_add_u64 v[16:17], v[20:21], 0, v[24:25]
	global_store_short v[16:17], v26, off
	v_add_f32_e32 v16, v18, v14
	v_lshlrev_b32_e32 v17, 16, v105
	v_mul_f32_e32 v16, v16, v17
	v_lshlrev_b32_e32 v17, 16, v104
	v_mul_f32_e32 v16, v16, v17
	v_or_b32_e32 v26, 0x1000, v22
	v_mov_b32_e32 v27, v23
	v_cvt_pk_bf16_f32 v18, v16, s0
	v_lshl_add_u64 v[16:17], v[20:21], 0, v[26:27]
	global_store_short v[16:17], v18, off
	v_add_f32_e32 v16, v19, v15
	v_lshlrev_b32_e32 v17, 16, v103
	v_mul_f32_e32 v16, v16, v17
	v_lshlrev_b32_e32 v17, 16, v102
	v_mul_f32_e32 v16, v16, v17
	v_or_b32_e32 v28, 0x1800, v22
	v_mov_b32_e32 v29, v23
	v_cvt_pk_bf16_f32 v18, v16, s0
	v_lshl_add_u64 v[16:17], v[20:21], 0, v[28:29]
	global_store_short v[16:17], v18, off
	v_add_f32_e32 v8, v8, v12
	v_lshlrev_b32_e32 v16, 16, v101
	v_mul_f32_e32 v8, v8, v16
	v_lshlrev_b32_e32 v16, 16, v100
	v_mul_f32_e32 v8, v8, v16
	v_lshl_add_u64 v[16:17], s[24:25], 0, v[22:23]
	v_cvt_pk_bf16_f32 v8, v8, s0
	v_lshl_add_u64 v[18:19], v[16:17], 0, v[190:191]
	global_store_short v[18:19], v8, off
	v_add_f32_e32 v8, v9, v13
	v_lshlrev_b32_e32 v9, 16, v99
	v_mul_f32_e32 v8, v8, v9
	v_lshlrev_b32_e32 v9, 16, v98
	v_mul_f32_e32 v8, v8, v9
	v_cvt_pk_bf16_f32 v20, v8, s0
	v_lshl_add_u64 v[8:9], s[24:25], 0, v[24:25]
	v_lshl_add_u64 v[18:19], v[8:9], 0, v[190:191]
	global_store_short v[18:19], v20, off
	v_add_f32_e32 v10, v10, v14
	v_lshlrev_b32_e32 v18, 16, v97
	v_mul_f32_e32 v10, v10, v18
	v_lshlrev_b32_e32 v18, 16, v96
	v_mul_f32_e32 v10, v10, v18
	v_lshl_add_u64 v[18:19], s[24:25], 0, v[26:27]
	v_cvt_pk_bf16_f32 v10, v10, s0
	v_lshl_add_u64 v[20:21], v[18:19], 0, v[190:191]
	global_store_short v[20:21], v10, off
	v_add_f32_e32 v10, v11, v15
	v_lshlrev_b32_e32 v11, 16, v95
	v_mul_f32_e32 v10, v10, v11
	v_lshlrev_b32_e32 v11, 16, v94
	v_mul_f32_e32 v10, v10, v11
	v_cvt_pk_bf16_f32 v22, v10, s0
	v_lshl_add_u64 v[10:11], s[24:25], 0, v[28:29]
	v_lshl_add_u64 v[20:21], v[10:11], 0, v[190:191]
	global_store_short v[20:21], v22, off
	v_add_f32_e32 v4, v4, v12
	v_lshlrev_b32_e32 v20, 16, v93
	v_mul_f32_e32 v4, v4, v20
	v_lshlrev_b32_e32 v20, 16, v92
	v_mul_f32_e32 v4, v4, v20
	v_or_b32_e32 v190, 64, v32
	v_cvt_pk_bf16_f32 v4, v4, s0
	v_lshl_add_u64 v[20:21], v[16:17], 0, v[190:191]
	global_store_short v[20:21], v4, off
	v_add_f32_e32 v4, v5, v13
	v_lshlrev_b32_e32 v5, 16, v88
	v_mul_f32_e32 v4, v4, v5
	v_lshlrev_b32_e32 v5, 16, v87
	v_mul_f32_e32 v4, v4, v5
	v_cvt_pk_bf16_f32 v20, v4, s0
	v_lshl_add_u64 v[4:5], v[8:9], 0, v[190:191]
	global_store_short v[4:5], v20, off
	v_add_f32_e32 v4, v6, v14
	v_lshlrev_b32_e32 v5, 16, v85
	v_mul_f32_e32 v4, v4, v5
	v_lshlrev_b32_e32 v5, 16, v84
	v_mul_f32_e32 v4, v4, v5
	v_cvt_pk_bf16_f32 v6, v4, s0
	v_lshl_add_u64 v[4:5], v[18:19], 0, v[190:191]
	global_store_short v[4:5], v6, off
	v_add_f32_e32 v4, v7, v15
	v_lshlrev_b32_e32 v5, 16, v83
	v_mul_f32_e32 v4, v4, v5
	v_lshlrev_b32_e32 v5, 16, v82
	v_mul_f32_e32 v4, v4, v5
	v_cvt_pk_bf16_f32 v6, v4, s0
	v_lshl_add_u64 v[4:5], v[10:11], 0, v[190:191]
	global_store_short v[4:5], v6, off
	v_add_f32_e32 v0, v0, v12
	v_lshlrev_b32_e32 v4, 16, v41
	v_mul_f32_e32 v0, v0, v4
	v_lshlrev_b32_e32 v4, 16, v89
	v_mul_f32_e32 v0, v0, v4
	v_or_b32_e32 v190, 0x60, v32
	v_cvt_pk_bf16_f32 v0, v0, s0
	v_lshl_add_u64 v[4:5], v[16:17], 0, v[190:191]
	global_store_short v[4:5], v0, off
	v_add_f32_e32 v0, v1, v13
	v_lshlrev_b32_e32 v1, 16, v86
	v_mul_f32_e32 v0, v0, v1
	v_lshlrev_b32_e32 v1, 16, v91
	v_mul_f32_e32 v0, v0, v1
	v_cvt_pk_bf16_f32 v4, v0, s0
	v_lshl_add_u64 v[0:1], v[8:9], 0, v[190:191]
	global_store_short v[0:1], v4, off
	v_add_f32_e32 v0, v2, v14
	v_lshlrev_b32_e32 v1, 16, v90
	v_mul_f32_e32 v0, v0, v1
	v_lshlrev_b32_e32 v1, 16, v71
	v_mul_f32_e32 v0, v0, v1
	v_cvt_pk_bf16_f32 v2, v0, s0
	v_lshl_add_u64 v[0:1], v[18:19], 0, v[190:191]
	global_store_short v[0:1], v2, off
	v_add_f32_e32 v0, v3, v15
	v_lshlrev_b32_e32 v1, 16, v70
	v_mul_f32_e32 v0, v0, v1
	v_lshlrev_b32_e32 v1, 16, v68
	v_mul_f32_e32 v0, v0, v1
	v_cvt_pk_bf16_f32 v2, v0, s0
	v_lshl_add_u64 v[0:1], v[10:11], 0, v[190:191]
	global_store_short v[0:1], v2, off
	s_barrier
	s_cbranch_scc1 .LBB0_554
.LBB0_546:
	s_add_i32 s2, s13, s60
	s_cmpk_lt_i32 s2, 0x200
	s_cselect_b32 s2, s2, -1
	s_cmp_lt_i32 s2, 0
	s_cselect_b32 s2, s13, s2
	s_ashr_i32 s20, s13, 7
	v_mov_b32_e32 v143, v184
	s_ashr_i32 s21, s20, 31
	s_lshl_b32 s3, s13, 5
	s_lshl_b64 s[20:21], s[20:21], 12
	v_ashrrev_i32_e32 v40, 2, v143
	s_and_b32 s3, s3, 0xf80
	v_ashrrev_i32_e32 v41, 31, v40
	v_lshlrev_b32_e32 v0, 4, v143
	s_or_b32 s20, s20, s3
	v_and_b32_e32 v146, 48, v0
	v_lshl_add_u64 v[0:1], s[20:21], 0, v[40:41]
	v_mov_b64_e32 v[16:17], s[26:27]
	v_mad_u64_u32 v[2:3], s[34:35], v0, s70, v[16:17]
	s_and_b32 s15, s13, 3
	s_ashr_i32 s34, s2, 7
	v_mad_i32_i24 v3, v1, s70, v3
	s_lshl_b32 s80, s15, 7
	s_and_b32 s14, s2, 3
	s_ashr_i32 s35, s34, 31
	s_lshl_b32 s2, s2, 5
	v_lshl_add_u64 v[0:1], v[2:3], 0, s[80:81]
	v_lshlrev_b32_e32 v190, 1, v146
	s_lshl_b64 s[34:35], s[34:35], 12
	s_and_b32 s2, s2, 0xf80
	v_lshl_add_u64 v[4:5], v[0:1], 0, v[190:191]
	s_or_b32 s34, s34, s2
	global_load_dwordx4 v[0:3], v[4:5], off offset:512
	global_load_dwordx4 v[12:15], v[4:5], off offset:528
	v_lshl_add_u64 v[4:5], s[34:35], 0, v[40:41]
	v_mad_u64_u32 v[6:7], s[36:37], v4, s70, v[16:17]
	v_mad_i32_i24 v7, v5, s70, v7
	s_lshl_b32 s80, s14, 7
	v_lshl_add_u64 v[4:5], v[6:7], 0, s[80:81]
	v_lshl_add_u64 v[8:9], v[4:5], 0, v[190:191]
	global_load_dwordx4 v[4:7], v[8:9], off offset:512
	s_nop 0
	global_load_dwordx4 v[8:11], v[8:9], off offset:528
	v_bfe_u32 v145, v143, 4, 2
	v_and_b32_e32 v38, -16, v40
	v_ashrrev_i32_e32 v39, 31, v38
	v_lshlrev_b32_e32 v142, 2, v145
	v_or_b32_e32 v18, v38, v142
	v_mov_b32_e32 v19, v39
	v_and_b32_e32 v144, 15, v143
	v_lshl_add_u64 v[36:37], v[18:19], 0, s[20:21]
	v_lshl_or_b32 v22, s15, 6, v144
	v_mad_u64_u32 v[20:21], s[20:21], v36, s70, v[16:17]
	v_mad_i32_i24 v21, v37, s70, v21
	v_lshlrev_b32_e32 v190, 1, v22
	v_lshl_add_u64 v[20:21], v[20:21], 0, v[190:191]
	v_add_co_u32_e32 v24, vcc, s76, v20
	s_movk_i32 s2, 0x5000
	s_nop 0
	v_addc_co_u32_e32 v25, vcc, 0, v21, vcc
	v_add_co_u32_e32 v26, vcc, s73, v20
	s_mov_b64 s[36:37], 0x1e00
	s_nop 0
	v_addc_co_u32_e32 v27, vcc, 0, v21, vcc
	s_mov_b64 s[40:41], 0x3c00
	v_add_co_u32_e32 v28, vcc, s2, v20
	global_load_ushort v141, v[20:21], off
	global_load_ushort v140, v[20:21], off offset:1024
	v_lshl_add_u64 v[22:23], v[20:21], 0, s[36:37]
	global_load_ushort v139, v[24:25], off offset:3584
	global_load_ushort v138, v[22:23], off offset:1024
	v_lshl_add_u64 v[24:25], v[20:21], 0, s[40:41]
	s_mov_b64 s[42:43], 0x5a00
	v_addc_co_u32_e32 v29, vcc, 0, v21, vcc
	global_load_ushort v137, v[26:27], off offset:3072
	global_load_ushort v136, v[24:25], off offset:1024
	v_lshl_add_u64 v[26:27], v[20:21], 0, s[42:43]
	global_load_ushort v135, v[28:29], off offset:2560
	global_load_ushort v134, v[26:27], off offset:1024
	global_load_ushort v133, v[20:21], off offset:32
	global_load_ushort v132, v[20:21], off offset:1056
	global_load_ushort v131, v[22:23], off offset:32
	global_load_ushort v130, v[22:23], off offset:1056
	global_load_ushort v129, v[24:25], off offset:32
	global_load_ushort v128, v[24:25], off offset:1056
	global_load_ushort v127, v[26:27], off offset:32
	global_load_ushort v126, v[26:27], off offset:1056
	global_load_ushort v120, v[20:21], off offset:64
	global_load_ushort v119, v[20:21], off offset:1088
	global_load_ushort v117, v[22:23], off offset:64
	global_load_ushort v116, v[22:23], off offset:1088
	global_load_ushort v114, v[24:25], off offset:64
	global_load_ushort v113, v[24:25], off offset:1088
	global_load_ushort v112, v[26:27], off offset:64
	global_load_ushort v111, v[26:27], off offset:1088
	global_load_ushort v110, v[20:21], off offset:96
	global_load_ushort v118, v[20:21], off offset:1120
	global_load_ushort v115, v[22:23], off offset:96
	global_load_ushort v122, v[22:23], off offset:1120
	global_load_ushort v121, v[24:25], off offset:96
	global_load_ushort v124, v[24:25], off offset:1120
	global_load_ushort v123, v[26:27], off offset:96
	global_load_ushort v125, v[26:27], off offset:1120
	v_lshl_add_u64 v[34:35], v[18:19], 0, s[34:35]
	v_lshl_or_b32 v18, s14, 6, v144
	v_mad_u64_u32 v[16:17], s[20:21], v34, s70, v[16:17]
	v_mad_i32_i24 v17, v35, s70, v17
	v_lshlrev_b32_e32 v32, 1, v18
	v_mov_b32_e32 v33, v191
	v_lshl_add_u64 v[16:17], v[16:17], 0, v[32:33]
	v_add_co_u32_e32 v20, vcc, s76, v16
	global_load_ushort v109, v[16:17], off
	global_load_ushort v108, v[16:17], off offset:1024
	v_addc_co_u32_e32 v21, vcc, 0, v17, vcc
	v_lshl_add_u64 v[18:19], v[16:17], 0, s[36:37]
	global_load_ushort v107, v[20:21], off offset:3584
	global_load_ushort v106, v[18:19], off offset:1024
	v_add_co_u32_e32 v20, vcc, s73, v16
	v_lshl_add_u64 v[70:71], v[16:17], 0, s[40:41]
	s_nop 0
	v_addc_co_u32_e32 v21, vcc, 0, v17, vcc
	global_load_ushort v105, v[20:21], off offset:3072
	global_load_ushort v104, v[70:71], off offset:1024
	v_add_co_u32_e32 v20, vcc, s2, v16
	v_lshl_add_u64 v[68:69], v[16:17], 0, s[42:43]
	s_nop 0
	v_addc_co_u32_e32 v21, vcc, 0, v17, vcc
	global_load_ushort v103, v[20:21], off offset:2560
	global_load_ushort v102, v[68:69], off offset:1024
	global_load_ushort v101, v[16:17], off offset:32
	global_load_ushort v100, v[16:17], off offset:1056
	global_load_ushort v99, v[18:19], off offset:32
	global_load_ushort v98, v[18:19], off offset:1056
	global_load_ushort v97, v[70:71], off offset:32
	global_load_ushort v96, v[70:71], off offset:1056
	global_load_ushort v95, v[68:69], off offset:32
	global_load_ushort v94, v[68:69], off offset:1056
	global_load_ushort v93, v[16:17], off offset:64
	global_load_ushort v92, v[16:17], off offset:1088
	global_load_ushort v88, v[18:19], off offset:64
	global_load_ushort v87, v[18:19], off offset:1088
	global_load_ushort v85, v[70:71], off offset:64
	global_load_ushort v84, v[70:71], off offset:1088
	global_load_ushort v83, v[68:69], off offset:64
	global_load_ushort v82, v[68:69], off offset:1088
	global_load_ushort v41, v[16:17], off offset:96
	global_load_ushort v89, v[16:17], off offset:1120
	global_load_ushort v86, v[18:19], off offset:96
	global_load_ushort v91, v[18:19], off offset:1120
	global_load_ushort v90, v[70:71], off offset:96
	v_and_b32_e32 v17, 64, v227
	v_xor_b32_e32 v16, 1, v227
	v_add_u32_e32 v17, 64, v17
	v_cmp_lt_i32_e32 vcc, v16, v17
	s_lshl_b32 s34, s15, 8
	s_mov_b32 s35, s81
	s_waitcnt vmcnt(62)
	v_lshlrev_b32_e32 v25, 16, v0
	v_and_b32_e32 v27, 0xffff0000, v0
	v_lshlrev_b32_e32 v51, 16, v1
	v_and_b32_e32 v53, 0xffff0000, v1
	v_lshlrev_b32_e32 v55, 16, v2
	v_and_b32_e32 v153, 0xffff0000, v2
	v_lshlrev_b32_e32 v155, 16, v3
	v_lshlrev_b32_e32 v45, 16, v12
	v_lshlrev_b32_e32 v24, 16, v4
	v_and_b32_e32 v26, 0xffff0000, v4
	v_pk_add_f32 v[0:1], v[24:25], 0 op_sel_hi:[1,0]
	v_lshlrev_b32_e32 v50, 16, v5
	v_pk_add_f32 v[0:1], v[0:1], v[26:27]
	v_and_b32_e32 v52, 0xffff0000, v5
	v_pk_add_f32 v[0:1], v[0:1], v[50:51]
	v_lshlrev_b32_e32 v54, 16, v6
	v_pk_add_f32 v[0:1], v[0:1], v[52:53]
	v_and_b32_e32 v152, 0xffff0000, v6
	v_pk_add_f32 v[0:1], v[0:1], v[54:55]
	v_lshlrev_b32_e32 v154, 16, v7
	v_pk_add_f32 v[0:1], v[0:1], v[152:153]
	s_waitcnt vmcnt(61)
	v_lshlrev_b32_e32 v49, 16, v8
	v_and_b32_e32 v157, 0xffff0000, v3
	v_and_b32_e32 v156, 0xffff0000, v7
	v_pk_add_f32 v[0:1], v[0:1], v[154:155]
	v_and_b32_e32 v44, 0xffff0000, v12
	v_and_b32_e32 v48, 0xffff0000, v8
	v_pk_add_f32 v[0:1], v[0:1], v[156:157]
	v_mov_b32_e32 v2, v49
	v_mov_b32_e32 v3, v45
	v_lshlrev_b32_e32 v43, 16, v13
	v_lshlrev_b32_e32 v47, 16, v9
	v_pk_add_f32 v[0:1], v[0:1], v[2:3]
	v_mov_b32_e32 v2, v48
	v_mov_b32_e32 v3, v44
	v_and_b32_e32 v42, 0xffff0000, v13
	v_and_b32_e32 v46, 0xffff0000, v9
	v_pk_add_f32 v[0:1], v[0:1], v[2:3]
	v_mov_b32_e32 v2, v47
	v_mov_b32_e32 v3, v43
	v_lshlrev_b32_e32 v31, 16, v14
	v_lshlrev_b32_e32 v151, 16, v10
	v_pk_add_f32 v[0:1], v[0:1], v[2:3]
	v_mov_b32_e32 v2, v46
	v_mov_b32_e32 v3, v42
	v_and_b32_e32 v30, 0xffff0000, v14
	v_and_b32_e32 v150, 0xffff0000, v10
	v_pk_add_f32 v[0:1], v[0:1], v[2:3]
	v_mov_b32_e32 v2, v151
	v_mov_b32_e32 v3, v31
	v_lshlrev_b32_e32 v29, 16, v15
	v_lshlrev_b32_e32 v149, 16, v11
	v_pk_add_f32 v[0:1], v[0:1], v[2:3]
	v_mov_b32_e32 v2, v150
	v_mov_b32_e32 v3, v30
	v_and_b32_e32 v28, 0xffff0000, v15
	v_and_b32_e32 v148, 0xffff0000, v11
	v_pk_add_f32 v[0:1], v[0:1], v[2:3]
	v_mov_b32_e32 v2, v149
	v_mov_b32_e32 v3, v29
	v_cndmask_b32_e32 v16, v227, v16, vcc
	v_pk_add_f32 v[0:1], v[0:1], v[2:3]
	v_mov_b32_e32 v2, v148
	v_mov_b32_e32 v3, v28
	v_lshlrev_b32_e32 v33, 2, v16
	v_xor_b32_e32 v16, 2, v227
	v_pk_add_f32 v[4:5], v[0:1], v[2:3]
	v_cmp_lt_i32_e32 vcc, v16, v17
	ds_bpermute_b32 v7, v33, v5
	ds_bpermute_b32 v6, v33, v4
	v_cndmask_b32_e32 v16, v227, v16, vcc
	v_lshlrev_b32_e32 v147, 2, v16
	v_lshlrev_b32_e32 v16, 2, v146
	v_mov_b32_e32 v17, v191
	v_lshl_add_u64 v[64:65], s[18:19], 0, v[16:17]
	v_lshl_add_u64 v[66:67], s[28:29], 0, v[16:17]
	v_lshl_add_u64 v[158:159], v[64:65], 0, s[34:35]
	v_lshl_add_u64 v[160:161], v[66:67], 0, s[34:35]
	global_load_dwordx4 v[0:3], v[158:159], off offset:32
	global_load_dwordx4 v[8:11], v[158:159], off offset:16
	s_waitcnt lgkmcnt(0)
	v_pk_add_f32 v[56:57], v[4:5], v[6:7]
	global_load_dwordx4 v[16:19], v[158:159], off
	global_load_dwordx4 v[4:7], v[160:161], off offset:32
	global_load_dwordx4 v[12:15], v[160:161], off offset:16
	global_load_dwordx4 v[20:23], v[160:161], off
	ds_bpermute_b32 v59, v147, v57
	ds_bpermute_b32 v58, v147, v56
	s_lshl_b32 s20, s14, 8
	s_mov_b32 s21, s81
	s_waitcnt lgkmcnt(0)
	v_pk_add_f32 v[162:163], v[56:57], v[58:59]
	s_nop 0
	v_pk_fma_f32 v[62:63], v[162:163], s[8:9], v[26:27] op_sel_hi:[1,0,1] neg_lo:[1,0,0] neg_hi:[1,0,0]
	v_pk_fma_f32 v[72:73], v[162:163], s[8:9], v[24:25] op_sel_hi:[1,0,1] neg_lo:[1,0,0] neg_hi:[1,0,0]
	v_pk_mul_f32 v[24:25], v[62:63], v[62:63]
	v_pk_fma_f32 v[60:61], v[162:163], s[8:9], v[50:51] op_sel_hi:[1,0,1] neg_lo:[1,0,0] neg_hi:[1,0,0]
	v_pk_fma_f32 v[24:25], v[72:73], v[72:73], v[24:25]
	v_pk_fma_f32 v[58:59], v[162:163], s[8:9], v[52:53] op_sel_hi:[1,0,1] neg_lo:[1,0,0] neg_hi:[1,0,0]
	v_pk_fma_f32 v[24:25], v[60:61], v[60:61], v[24:25]
	v_pk_fma_f32 v[56:57], v[162:163], s[8:9], v[54:55] op_sel_hi:[1,0,1] neg_lo:[1,0,0] neg_hi:[1,0,0]
	v_pk_fma_f32 v[24:25], v[58:59], v[58:59], v[24:25]
	v_pk_mul_f32 v[164:165], v[162:163], s[8:9] op_sel_hi:[1,0]
	v_pk_fma_f32 v[24:25], v[56:57], v[56:57], v[24:25]
	v_pk_fma_f32 v[54:55], v[162:163], s[8:9], v[152:153] op_sel_hi:[1,0,1] neg_lo:[1,0,0] neg_hi:[1,0,0]
	v_pk_add_f32 v[80:81], v[44:45], v[164:165] op_sel:[0,1] neg_lo:[0,1] neg_hi:[0,1]
	v_pk_fma_f32 v[24:25], v[54:55], v[54:55], v[24:25]
	v_pk_fma_f32 v[52:53], v[162:163], s[8:9], v[154:155] op_sel_hi:[1,0,1] neg_lo:[1,0,0] neg_hi:[1,0,0]
	v_pk_add_f32 v[48:49], v[48:49], v[164:165] op_sel_hi:[1,0] neg_lo:[0,1] neg_hi:[0,1]
	v_pk_mul_f32 v[166:167], v[80:81], v[80:81]
	v_pk_fma_f32 v[24:25], v[52:53], v[52:53], v[24:25]
	v_pk_fma_f32 v[50:51], v[162:163], s[8:9], v[156:157] op_sel_hi:[1,0,1] neg_lo:[1,0,0] neg_hi:[1,0,0]
	v_pk_mul_f32 v[26:27], v[48:49], v[48:49]
	v_pk_add_f32 v[78:79], v[42:43], v[164:165] op_sel:[0,1] neg_lo:[0,1] neg_hi:[0,1]
	v_pk_fma_f32 v[24:25], v[50:51], v[50:51], v[24:25]
	v_mov_b32_e32 v42, v27
	v_mov_b32_e32 v43, v167
	v_pk_add_f32 v[46:47], v[46:47], v[164:165] op_sel_hi:[1,0] neg_lo:[0,1] neg_hi:[0,1]
	v_pk_mul_f32 v[168:169], v[78:79], v[78:79]
	v_pk_add_f32 v[24:25], v[42:43], v[24:25]
	v_pk_mul_f32 v[152:153], v[46:47], v[46:47]
	v_mov_b32_e32 v27, v166
	v_pk_add_f32 v[76:77], v[30:31], v[164:165] op_sel:[0,1] neg_lo:[0,1] neg_hi:[0,1]
	v_pk_add_f32 v[44:45], v[150:151], v[164:165] op_sel_hi:[1,0] neg_lo:[0,1] neg_hi:[0,1]
	v_pk_add_f32 v[24:25], v[26:27], v[24:25]
	v_mov_b32_e32 v26, v153
	v_mov_b32_e32 v27, v169
	v_pk_mul_f32 v[30:31], v[76:77], v[76:77]
	v_pk_mul_f32 v[150:151], v[44:45], v[44:45]
	v_pk_add_f32 v[24:25], v[26:27], v[24:25]
	v_mov_b32_e32 v153, v168
	v_pk_add_f32 v[74:75], v[28:29], v[164:165] op_sel:[0,1] neg_lo:[0,1] neg_hi:[0,1]
	v_pk_add_f32 v[42:43], v[148:149], v[164:165] op_sel_hi:[1,0] neg_lo:[0,1] neg_hi:[0,1]
	v_pk_add_f32 v[24:25], v[152:153], v[24:25]
	v_mov_b32_e32 v26, v151
	v_mov_b32_e32 v27, v31
	v_pk_mul_f32 v[28:29], v[74:75], v[74:75]
	v_pk_mul_f32 v[148:149], v[42:43], v[42:43]
	v_pk_add_f32 v[24:25], v[26:27], v[24:25]
	v_mov_b32_e32 v151, v30
	v_pk_add_f32 v[24:25], v[150:151], v[24:25]
	v_mov_b32_e32 v26, v149
	v_mov_b32_e32 v27, v29
	v_pk_add_f32 v[24:25], v[26:27], v[24:25]
	v_mov_b32_e32 v149, v28
	v_pk_add_f32 v[148:149], v[148:149], v[24:25]
	ds_bpermute_b32 v151, v33, v149
	ds_bpermute_b32 v150, v33, v148
	global_load_dwordx4 v[24:27], v[158:159], off offset:48
	global_load_dwordx4 v[28:31], v[160:161], off offset:48
	s_nop 0
	global_load_ushort v71, v[70:71], off offset:1120
	s_nop 0
	global_load_ushort v70, v[68:69], off offset:96
	v_lshlrev_b32_e32 v33, 1, v40
	global_load_ushort v68, v[68:69], off offset:1120
	v_mul_u32_u24_e32 v69, 0x110, v146
	s_waitcnt lgkmcnt(0)
	v_pk_add_f32 v[148:149], v[148:149], v[150:151]
	ds_bpermute_b32 v151, v147, v149
	ds_bpermute_b32 v150, v147, v148
	v_add3_u32 v33, 0, v33, v69
	v_lshl_add_u64 v[160:161], v[64:65], 0, s[20:21]
	v_lshl_add_u64 v[162:163], v[66:67], 0, s[20:21]
	s_waitcnt lgkmcnt(0)
	v_pk_add_f32 v[146:147], v[148:149], v[150:151]
	s_nop 0
	v_pk_fma_f32 v[158:159], v[146:147], s[8:9], v[192:193] op_sel_hi:[1,0,0]
	global_load_dwordx4 v[64:67], v[160:161], off
	global_load_dwordx4 v[146:149], v[162:163], off
	v_mul_f32_e32 v69, 0x4b800000, v159
	v_cmp_gt_f32_e32 vcc, s93, v159
	v_cmp_gt_f32_e64 s[40:41], s93, v158
	s_nop 0
	v_cndmask_b32_e32 v69, v159, v69, vcc
	v_rsq_f32_e32 v69, v69
	s_nop 0
	v_mul_f32_e32 v150, 0x45800000, v69
	v_cndmask_b32_e32 v69, v69, v150, vcc
	v_mul_f32_e32 v73, v73, v69
	s_waitcnt vmcnt(7)
	v_fma_f32 v16, v16, v73, v20
	v_cvt_pk_bf16_f32 v16, v16, s0
	ds_write_b16 v33, v16
	v_mul_f32_e32 v16, v63, v69
	v_fma_f32 v16, v17, v16, v21
	v_cvt_pk_bf16_f32 v16, v16, s0
	ds_write_b16 v33, v16 offset:272
	v_mul_f32_e32 v16, v61, v69
	v_fma_f32 v16, v18, v16, v22
	global_load_dwordx4 v[150:153], v[160:161], off offset:16
	global_load_dwordx4 v[154:157], v[162:163], off offset:16
	v_cvt_pk_bf16_f32 v16, v16, s0
	ds_write_b16 v33, v16 offset:544
	v_mul_f32_e32 v16, v59, v69
	v_fmac_f32_e32 v23, v19, v16
	v_cvt_pk_bf16_f32 v16, v23, s0
	ds_write_b16 v33, v16 offset:816
	v_mul_f32_e32 v16, v57, v69
	v_fma_f32 v8, v8, v16, v12
	v_cvt_pk_bf16_f32 v8, v8, s0
	ds_write_b16 v33, v8 offset:1088
	v_mul_f32_e32 v8, v55, v69
	v_fma_f32 v8, v9, v8, v13
	v_cvt_pk_bf16_f32 v8, v8, s0
	ds_write_b16 v33, v8 offset:1360
	global_load_dwordx4 v[16:19], v[160:161], off offset:32
	global_load_dwordx4 v[20:23], v[162:163], off offset:32
	v_mul_f32_e32 v8, v53, v69
	v_fma_f32 v8, v10, v8, v14
	v_cvt_pk_bf16_f32 v8, v8, s0
	ds_write_b16 v33, v8 offset:1632
	v_mul_f32_e32 v8, v51, v69
	v_fmac_f32_e32 v15, v11, v8
	v_cvt_pk_bf16_f32 v8, v15, s0
	ds_write_b16 v33, v8 offset:1904
	v_mul_f32_e32 v8, v81, v69
	v_fma_f32 v0, v0, v8, v4
	v_cvt_pk_bf16_f32 v0, v0, s0
	ds_write_b16 v33, v0 offset:2176
	global_load_dwordx4 v[8:11], v[160:161], off offset:48
	global_load_dwordx4 v[12:15], v[162:163], off offset:48
	v_mul_f32_e32 v0, v80, v69
	v_fma_f32 v0, v0, v1, v5
	v_cvt_pk_bf16_f32 v0, v0, s0
	ds_write_b16 v33, v0 offset:2448
	v_mul_f32_e32 v0, v79, v69
	v_fma_f32 v0, v0, v2, v6
	v_cvt_pk_bf16_f32 v0, v0, s0
	ds_write_b16 v33, v0 offset:2720
	v_mul_f32_e32 v0, v78, v69
	v_fmac_f32_e32 v7, v0, v3
	v_cvt_pk_bf16_f32 v0, v7, s0
	ds_write_b16 v33, v0 offset:2992
	v_mul_f32_e32 v0, v77, v69
	v_mul_f32_e32 v1, 0x4b800000, v158
	s_waitcnt vmcnt(11)
	v_fma_f32 v0, v0, v24, v28
	v_cvt_pk_bf16_f32 v0, v0, s0
	ds_write_b16 v33, v0 offset:3264
	v_mul_f32_e32 v0, v76, v69
	v_fma_f32 v0, v0, v25, v29
	v_cvt_pk_bf16_f32 v0, v0, s0
	ds_write_b16 v33, v0 offset:3536
	v_mul_f32_e32 v0, v75, v69
	v_fma_f32 v0, v0, v26, v30
	v_cndmask_b32_e64 v1, v158, v1, s[40:41]
	v_cvt_pk_bf16_f32 v0, v0, s0
	v_rsq_f32_e32 v1, v1
	ds_write_b16 v33, v0 offset:3808
	v_mul_f32_e32 v0, v74, v69
	v_fmac_f32_e32 v31, v0, v27
	v_cvt_pk_bf16_f32 v0, v31, s0
	ds_write_b16 v33, v0 offset:4080
	v_mul_f32_e32 v0, 0x45800000, v1
	v_cndmask_b32_e64 v0, v1, v0, s[40:41]
	v_mul_f32_e32 v1, v72, v0
	s_waitcnt vmcnt(6)
	v_fma_f32 v1, v64, v1, v146
	v_cvt_pk_bf16_f32 v1, v1, s0
	ds_write_b16 v33, v1 offset:17408
	v_mul_f32_e32 v1, v62, v0
	v_fma_f32 v1, v65, v1, v147
	v_cvt_pk_bf16_f32 v1, v1, s0
	ds_write_b16 v33, v1 offset:17680
	v_mul_f32_e32 v1, v60, v0
	v_fma_f32 v1, v66, v1, v148
	v_cvt_pk_bf16_f32 v1, v1, s0
	ds_write_b16 v33, v1 offset:17952
	v_mul_f32_e32 v1, v58, v0
	v_fmac_f32_e32 v149, v67, v1
	v_cvt_pk_bf16_f32 v1, v149, s0
	ds_write_b16 v33, v1 offset:18224
	v_mul_f32_e32 v1, v56, v0
	v_bfi_b32 v24, -16, v40, v143
	s_waitcnt vmcnt(4)
	v_fma_f32 v1, v150, v1, v154
	v_cvt_pk_bf16_f32 v1, v1, s0
	ds_write_b16 v33, v1 offset:18496
	v_mul_f32_e32 v1, v54, v0
	v_fma_f32 v1, v151, v1, v155
	v_cvt_pk_bf16_f32 v1, v1, s0
	ds_write_b16 v33, v1 offset:18768
	v_mul_f32_e32 v1, v52, v0
	v_fma_f32 v1, v152, v1, v156
	v_cvt_pk_bf16_f32 v1, v1, s0
	ds_write_b16 v33, v1 offset:19040
	v_mul_f32_e32 v1, v50, v0
	v_fmac_f32_e32 v157, v153, v1
	v_cvt_pk_bf16_f32 v1, v157, s0
	ds_write_b16 v33, v1 offset:19312
	v_mul_f32_e32 v1, v49, v0
	s_waitcnt vmcnt(2)
	v_fma_f32 v1, v16, v1, v20
	v_cvt_pk_bf16_f32 v1, v1, s0
	ds_write_b16 v33, v1 offset:19584
	v_mul_f32_e32 v1, v48, v0
	v_fma_f32 v1, v1, v17, v21
	v_cvt_pk_bf16_f32 v1, v1, s0
	ds_write_b16 v33, v1 offset:19856
	v_mul_f32_e32 v1, v47, v0
	v_fma_f32 v1, v1, v18, v22
	v_cvt_pk_bf16_f32 v1, v1, s0
	ds_write_b16 v33, v1 offset:20128
	v_mul_f32_e32 v1, v46, v0
	v_fmac_f32_e32 v23, v1, v19
	v_cvt_pk_bf16_f32 v1, v23, s0
	ds_write_b16 v33, v1 offset:20400
	v_mul_f32_e32 v1, v45, v0
	s_waitcnt vmcnt(0)
	v_fma_f32 v1, v1, v8, v12
	v_cvt_pk_bf16_f32 v1, v1, s0
	ds_write_b16 v33, v1 offset:20672
	v_mul_f32_e32 v1, v44, v0
	v_fma_f32 v1, v1, v9, v13
	v_cvt_pk_bf16_f32 v1, v1, s0
	ds_write_b16 v33, v1 offset:20944
	v_mul_f32_e32 v1, v43, v0
	v_mul_f32_e32 v0, v42, v0
	v_fma_f32 v1, v1, v10, v14
	v_fmac_f32_e32 v15, v0, v11
	v_cvt_pk_bf16_f32 v1, v1, s0
	v_cvt_pk_bf16_f32 v0, v15, s0
	v_ashrrev_i32_e32 v12, 7, v143
	v_lshlrev_b32_e32 v13, 3, v145
	v_mov_b32_e32 v19, 0
	v_add_u32_e32 v20, v38, v144
	ds_write_b16 v33, v1 offset:21216
	ds_write_b16 v33, v0 offset:21488
	v_cmp_lt_i32_e32 vcc, -1, v12
	v_mul_u32_u24_e32 v28, 0x110, v144
	v_lshlrev_b32_e32 v29, 4, v145
	v_lshlrev_b32_e32 v27, 1, v143
	v_add_u32_e32 v25, 1, v12
	v_add_u32_e32 v26, 7, v13
	v_ashrrev_i32_e32 v21, 31, v20
	v_mov_b32_e32 v18, v19
	v_mov_b32_e32 v17, v19
	v_mov_b32_e32 v16, v19
	v_mov_b32_e32 v11, v19
	v_mov_b32_e32 v10, v19
	v_mov_b32_e32 v9, v19
	v_mov_b32_e32 v8, v19
	v_mov_b32_e32 v7, v19
	v_mov_b32_e32 v6, v19
	v_mov_b32_e32 v5, v19
	v_mov_b32_e32 v4, v19
	v_mov_b32_e32 v3, v19
	v_mov_b32_e32 v2, v19
	v_mov_b32_e32 v1, v19
	v_mov_b32_e32 v0, v19
	v_mov_b32_e32 v244, 0
	v_lshlrev_b32_e32 v246, 16, v202
	v_and_b32_e32 v247, 0xffff0000, v202
	v_mul_f32_e32 v245, v246, v246
	v_fmac_f32_e32 v245, v247, v247
	v_lshlrev_b32_e32 v246, 16, v203
	v_and_b32_e32 v247, 0xffff0000, v203
	v_fmac_f32_e32 v245, v246, v246
	v_fmac_f32_e32 v245, v247, v247
	v_lshlrev_b32_e32 v246, 16, v204
	v_and_b32_e32 v247, 0xffff0000, v204
	v_fmac_f32_e32 v245, v246, v246
	v_fmac_f32_e32 v245, v247, v247
	v_lshlrev_b32_e32 v246, 16, v205
	v_and_b32_e32 v247, 0xffff0000, v205
	v_fmac_f32_e32 v245, v246, v246
	v_fmac_f32_e32 v245, v247, v247
	v_max_f32_e32 v244, v244, v245
	v_lshlrev_b32_e32 v246, 16, v206
	v_and_b32_e32 v247, 0xffff0000, v206
	v_mul_f32_e32 v245, v246, v246
	v_fmac_f32_e32 v245, v247, v247
	v_lshlrev_b32_e32 v246, 16, v207
	v_and_b32_e32 v247, 0xffff0000, v207
	v_fmac_f32_e32 v245, v246, v246
	v_fmac_f32_e32 v245, v247, v247
	v_lshlrev_b32_e32 v246, 16, v208
	v_and_b32_e32 v247, 0xffff0000, v208
	v_fmac_f32_e32 v245, v246, v246
	v_fmac_f32_e32 v245, v247, v247
	v_lshlrev_b32_e32 v246, 16, v209
	v_and_b32_e32 v247, 0xffff0000, v209
	v_fmac_f32_e32 v245, v246, v246
	v_fmac_f32_e32 v245, v247, v247
	v_max_f32_e32 v244, v244, v245
	v_lshlrev_b32_e32 v246, 16, v210
	v_and_b32_e32 v247, 0xffff0000, v210
	v_mul_f32_e32 v245, v246, v246
	v_fmac_f32_e32 v245, v247, v247
	v_lshlrev_b32_e32 v246, 16, v211
	v_and_b32_e32 v247, 0xffff0000, v211
	v_fmac_f32_e32 v245, v246, v246
	v_fmac_f32_e32 v245, v247, v247
	v_lshlrev_b32_e32 v246, 16, v212
	v_and_b32_e32 v247, 0xffff0000, v212
	v_fmac_f32_e32 v245, v246, v246
	v_fmac_f32_e32 v245, v247, v247
	v_lshlrev_b32_e32 v246, 16, v213
	v_and_b32_e32 v247, 0xffff0000, v213
	v_fmac_f32_e32 v245, v246, v246
	v_fmac_f32_e32 v245, v247, v247
	v_max_f32_e32 v244, v244, v245
	v_lshlrev_b32_e32 v246, 16, v214
	v_and_b32_e32 v247, 0xffff0000, v214
	v_mul_f32_e32 v245, v246, v246
	v_fmac_f32_e32 v245, v247, v247
	v_lshlrev_b32_e32 v246, 16, v215
	v_and_b32_e32 v247, 0xffff0000, v215
	v_fmac_f32_e32 v245, v246, v246
	v_fmac_f32_e32 v245, v247, v247
	v_lshlrev_b32_e32 v246, 16, v216
	v_and_b32_e32 v247, 0xffff0000, v216
	v_fmac_f32_e32 v245, v246, v246
	v_fmac_f32_e32 v245, v247, v247
	v_lshlrev_b32_e32 v246, 16, v217
	v_and_b32_e32 v247, 0xffff0000, v217
	v_fmac_f32_e32 v245, v246, v246
	v_fmac_f32_e32 v245, v247, v247
	v_max_f32_e32 v244, v244, v245
	v_lshlrev_b32_e32 v246, 16, v218
	v_and_b32_e32 v247, 0xffff0000, v218
	v_mul_f32_e32 v245, v246, v246
	v_fmac_f32_e32 v245, v247, v247
	v_lshlrev_b32_e32 v246, 16, v219
	v_and_b32_e32 v247, 0xffff0000, v219
	v_fmac_f32_e32 v245, v246, v246
	v_fmac_f32_e32 v245, v247, v247
	v_lshlrev_b32_e32 v246, 16, v220
	v_and_b32_e32 v247, 0xffff0000, v220
	v_fmac_f32_e32 v245, v246, v246
	v_fmac_f32_e32 v245, v247, v247
	v_lshlrev_b32_e32 v246, 16, v221
	v_and_b32_e32 v247, 0xffff0000, v221
	v_fmac_f32_e32 v245, v246, v246
	v_fmac_f32_e32 v245, v247, v247
	v_max_f32_e32 v244, v244, v245
	v_lshlrev_b32_e32 v246, 16, v230
	v_and_b32_e32 v247, 0xffff0000, v230
	v_mul_f32_e32 v245, v246, v246
	v_fmac_f32_e32 v245, v247, v247
	v_lshlrev_b32_e32 v246, 16, v231
	v_and_b32_e32 v247, 0xffff0000, v231
	v_fmac_f32_e32 v245, v246, v246
	v_fmac_f32_e32 v245, v247, v247
	v_lshlrev_b32_e32 v246, 16, v232
	v_and_b32_e32 v247, 0xffff0000, v232
	v_fmac_f32_e32 v245, v246, v246
	v_fmac_f32_e32 v245, v247, v247
	v_lshlrev_b32_e32 v246, 16, v233
	v_and_b32_e32 v247, 0xffff0000, v233
	v_fmac_f32_e32 v245, v246, v246
	v_fmac_f32_e32 v245, v247, v247
	v_max_f32_e32 v244, v244, v245
	v_lshlrev_b32_e32 v246, 16, v234
	v_and_b32_e32 v247, 0xffff0000, v234
	v_mul_f32_e32 v245, v246, v246
	v_fmac_f32_e32 v245, v247, v247
	v_lshlrev_b32_e32 v246, 16, v235
	v_and_b32_e32 v247, 0xffff0000, v235
	v_fmac_f32_e32 v245, v246, v246
	v_fmac_f32_e32 v245, v247, v247
	v_lshlrev_b32_e32 v246, 16, v236
	v_and_b32_e32 v247, 0xffff0000, v236
	v_fmac_f32_e32 v245, v246, v246
	v_fmac_f32_e32 v245, v247, v247
	v_lshlrev_b32_e32 v246, 16, v237
	v_and_b32_e32 v247, 0xffff0000, v237
	v_fmac_f32_e32 v245, v246, v246
	v_fmac_f32_e32 v245, v247, v247
	v_max_f32_e32 v244, v244, v245
	v_lshlrev_b32_e32 v246, 16, v238
	v_and_b32_e32 v247, 0xffff0000, v238
	v_mul_f32_e32 v245, v246, v246
	v_fmac_f32_e32 v245, v247, v247
	v_lshlrev_b32_e32 v246, 16, v239
	v_and_b32_e32 v247, 0xffff0000, v239
	v_fmac_f32_e32 v245, v246, v246
	v_fmac_f32_e32 v245, v247, v247
	v_lshlrev_b32_e32 v246, 16, v240
	v_and_b32_e32 v247, 0xffff0000, v240
	v_fmac_f32_e32 v245, v246, v246
	v_fmac_f32_e32 v245, v247, v247
	v_lshlrev_b32_e32 v246, 16, v241
	v_and_b32_e32 v247, 0xffff0000, v241
	v_fmac_f32_e32 v245, v246, v246
	v_fmac_f32_e32 v245, v247, v247
	v_max_f32_e32 v244, v244, v245
	v_and_b32_e32 v248, 63, v184
	v_lshlrev_b32_e32 v248, 2, v248
	v_xor_b32_e32 v249, 32, v248
	ds_bpermute_b32 v246, v249, v244
	s_waitcnt lgkmcnt(0)
	v_max_f32_e32 v244, v244, v246
	v_xor_b32_e32 v249, 64, v248
	ds_bpermute_b32 v246, v249, v244
	s_waitcnt lgkmcnt(0)
	v_max_f32_e32 v244, v244, v246
	v_xor_b32_e32 v249, 128, v248
	ds_bpermute_b32 v246, v249, v244
	s_waitcnt lgkmcnt(0)
	v_max_f32_e32 v244, v244, v246
	v_lshlrev_b32_e32 v248, 1, v248
	s_mov_b64 exec, 0xff
	global_atomic_umax v250, v248, v244, s[100:101] sc0
	s_mov_b64 exec, -1
	s_waitcnt lgkmcnt(0)
	s_barrier
	s_and_saveexec_b64 s[34:35], vcc
	s_cbranch_execz .LBB0_550
	s_and_b32 s2, s12, 3
	s_lshl_b32 s2, s2, 7
	s_add_i32 s20, s11, s2
	s_mov_b32 s21, s81
	v_lshl_add_u64 v[0:1], v[20:21], 0, s[20:21]
	v_lshlrev_b64 v[0:1], 9, v[0:1]
	s_movk_i32 s2, 0x60
	v_and_or_b32 v0, v27, s2, v0
	v_add_u32_e32 v14, 1, v12
	v_add_u32_e32 v15, 7, v13
	v_lshl_add_u64 v[12:13], s[30:31], 0, v[0:1]
	v_mov_b32_e32 v0, 0
	v_add3_u32 v22, v28, v29, 0
	s_mov_b64 s[36:37], 0
	v_mov_b32_e32 v1, v0
	v_mov_b32_e32 v2, v0
	v_mov_b32_e32 v3, v0
	v_mov_b32_e32 v4, v0
	v_mov_b32_e32 v5, v0
	v_mov_b32_e32 v6, v0
	v_mov_b32_e32 v7, v0
	v_mov_b32_e32 v8, v0
	v_mov_b32_e32 v9, v0
	v_mov_b32_e32 v10, v0
	v_mov_b32_e32 v11, v0
	v_mov_b32_e32 v16, v0
	v_mov_b32_e32 v17, v0
	v_mov_b32_e32 v18, v0
	v_mov_b32_e32 v19, v0
